# NSA loops: deferred-rescale decision from each lane's local max (no cross-half permlane exchange or max canonicalisation on the common path)
# speedup vs baseline: 1.0147x; 1.0147x over previous
.Lself0_join:
	v_fma_f32 v251, v0, s90, -v235
	ds_read_b128 v[86:89], v81 offset:26624
	ds_read_b128 v[82:85], v81 offset:31232
	v_cmp_ge_f32_e32 vcc, 0x41000000, v251
	s_cmp_eq_u64 vcc, exec
	s_cbranch_scc0 .Llazy0_resc
	v_mov_b32_e32 v236, v235
	v_mov_b32_e32 v0, 1.0

.Llazy0_resc:
	v_mov_b32_e32 v251, v0
	s_nop 1
	v_permlane32_swap_b32_e32 v0, v251
	v_max_f32_e32 v251, v251, v251
	v_max_f32_e32 v0, v0, v0
	v_max_f32_e32 v0, v0, v251
	v_mul_f32_e32 v0, 0x3e0293ee, v0
	v_max_f32_e32 v251, v235, v235
	v_max_f32_e32 v236, v251, v0
	v_sub_f32_e32 v0, v235, v236
	v_exp_f32_e32 v0, v0
	s_nop 0
	v_pk_mul_f32 v[78:79], v[78:79], v[0:1] op_sel_hi:[1,0]
	v_pk_mul_f32 v[76:77], v[76:77], v[0:1] op_sel_hi:[1,0]
	v_pk_mul_f32 v[74:75], v[74:75], v[0:1] op_sel_hi:[1,0]
	v_pk_mul_f32 v[72:73], v[72:73], v[0:1] op_sel_hi:[1,0]
	v_pk_mul_f32 v[70:71], v[70:71], v[0:1] op_sel_hi:[1,0]
	v_pk_mul_f32 v[68:69], v[68:69], v[0:1] op_sel_hi:[1,0]
	v_pk_mul_f32 v[66:67], v[66:67], v[0:1] op_sel_hi:[1,0]
	v_pk_mul_f32 v[64:65], v[64:65], v[0:1] op_sel_hi:[1,0]
	v_pk_mul_f32 v[62:63], v[62:63], v[0:1] op_sel_hi:[1,0]
	v_pk_mul_f32 v[60:61], v[60:61], v[0:1] op_sel_hi:[1,0]
	v_pk_mul_f32 v[58:59], v[58:59], v[0:1] op_sel_hi:[1,0]
	v_pk_mul_f32 v[56:57], v[56:57], v[0:1] op_sel_hi:[1,0]
	v_pk_mul_f32 v[54:55], v[54:55], v[0:1] op_sel_hi:[1,0]
	v_pk_mul_f32 v[52:53], v[52:53], v[0:1] op_sel_hi:[1,0]
	v_pk_mul_f32 v[50:51], v[50:51], v[0:1] op_sel_hi:[1,0]
	v_pk_mul_f32 v[48:49], v[48:49], v[0:1] op_sel_hi:[1,0]
	v_pk_mul_f32 v[46:47], v[46:47], v[0:1] op_sel_hi:[1,0]
	v_pk_mul_f32 v[44:45], v[44:45], v[0:1] op_sel_hi:[1,0]
	v_pk_mul_f32 v[42:43], v[42:43], v[0:1] op_sel_hi:[1,0]
	v_pk_mul_f32 v[40:41], v[40:41], v[0:1] op_sel_hi:[1,0]
	v_pk_mul_f32 v[38:39], v[38:39], v[0:1] op_sel_hi:[1,0]
	v_pk_mul_f32 v[36:37], v[36:37], v[0:1] op_sel_hi:[1,0]
	v_pk_mul_f32 v[34:35], v[34:35], v[0:1] op_sel_hi:[1,0]
	v_pk_mul_f32 v[32:33], v[32:33], v[0:1] op_sel_hi:[1,0]
	v_pk_mul_f32 v[30:31], v[30:31], v[0:1] op_sel_hi:[1,0]
	v_pk_mul_f32 v[28:29], v[28:29], v[0:1] op_sel_hi:[1,0]
	v_pk_mul_f32 v[26:27], v[26:27], v[0:1] op_sel_hi:[1,0]
	v_pk_mul_f32 v[24:25], v[24:25], v[0:1] op_sel_hi:[1,0]
	v_pk_mul_f32 v[22:23], v[22:23], v[0:1] op_sel_hi:[1,0]
	v_pk_mul_f32 v[20:21], v[20:21], v[0:1] op_sel_hi:[1,0]
	v_pk_mul_f32 v[18:19], v[18:19], v[0:1] op_sel_hi:[1,0]
	v_pk_mul_f32 v[16:17], v[16:17], v[0:1] op_sel_hi:[1,0]
	s_branch .LBB0_1213
.Llazy1_resc:
	v_mov_b32_e32 v251, v0
	s_nop 1
	v_permlane32_swap_b32_e32 v0, v251
	v_max_f32_e32 v251, v251, v251
	v_max_f32_e32 v0, v0, v0
	v_max_f32_e32 v0, v0, v251
	v_mul_f32_e32 v0, 0x3e0293ee, v0
	v_max_f32_e32 v251, v236, v236
	v_max_f32_e32 v235, v251, v0
	v_sub_f32_e32 v0, v236, v235
	v_exp_f32_e32 v0, v0
	s_nop 0
	v_pk_mul_f32 v[78:79], v[78:79], v[0:1] op_sel_hi:[1,0]
	v_pk_mul_f32 v[76:77], v[76:77], v[0:1] op_sel_hi:[1,0]
	v_pk_mul_f32 v[74:75], v[74:75], v[0:1] op_sel_hi:[1,0]
	v_pk_mul_f32 v[72:73], v[72:73], v[0:1] op_sel_hi:[1,0]
	v_pk_mul_f32 v[70:71], v[70:71], v[0:1] op_sel_hi:[1,0]
	v_pk_mul_f32 v[68:69], v[68:69], v[0:1] op_sel_hi:[1,0]
	v_pk_mul_f32 v[66:67], v[66:67], v[0:1] op_sel_hi:[1,0]
	v_pk_mul_f32 v[64:65], v[64:65], v[0:1] op_sel_hi:[1,0]
	v_pk_mul_f32 v[62:63], v[62:63], v[0:1] op_sel_hi:[1,0]
	v_pk_mul_f32 v[60:61], v[60:61], v[0:1] op_sel_hi:[1,0]
	v_pk_mul_f32 v[58:59], v[58:59], v[0:1] op_sel_hi:[1,0]
	v_pk_mul_f32 v[56:57], v[56:57], v[0:1] op_sel_hi:[1,0]
	v_pk_mul_f32 v[54:55], v[54:55], v[0:1] op_sel_hi:[1,0]
	v_pk_mul_f32 v[52:53], v[52:53], v[0:1] op_sel_hi:[1,0]
	v_pk_mul_f32 v[50:51], v[50:51], v[0:1] op_sel_hi:[1,0]
	v_pk_mul_f32 v[48:49], v[48:49], v[0:1] op_sel_hi:[1,0]
	v_pk_mul_f32 v[46:47], v[46:47], v[0:1] op_sel_hi:[1,0]
	v_pk_mul_f32 v[44:45], v[44:45], v[0:1] op_sel_hi:[1,0]
	v_pk_mul_f32 v[42:43], v[42:43], v[0:1] op_sel_hi:[1,0]
	v_pk_mul_f32 v[40:41], v[40:41], v[0:1] op_sel_hi:[1,0]
	v_pk_mul_f32 v[38:39], v[38:39], v[0:1] op_sel_hi:[1,0]
	v_pk_mul_f32 v[36:37], v[36:37], v[0:1] op_sel_hi:[1,0]
	v_pk_mul_f32 v[34:35], v[34:35], v[0:1] op_sel_hi:[1,0]
	v_pk_mul_f32 v[32:33], v[32:33], v[0:1] op_sel_hi:[1,0]
	v_pk_mul_f32 v[30:31], v[30:31], v[0:1] op_sel_hi:[1,0]
	v_pk_mul_f32 v[28:29], v[28:29], v[0:1] op_sel_hi:[1,0]
	v_pk_mul_f32 v[26:27], v[26:27], v[0:1] op_sel_hi:[1,0]
	v_pk_mul_f32 v[24:25], v[24:25], v[0:1] op_sel_hi:[1,0]
	v_pk_mul_f32 v[22:23], v[22:23], v[0:1] op_sel_hi:[1,0]
	v_pk_mul_f32 v[20:21], v[20:21], v[0:1] op_sel_hi:[1,0]
	v_pk_mul_f32 v[18:19], v[18:19], v[0:1] op_sel_hi:[1,0]
	v_pk_mul_f32 v[16:17], v[16:17], v[0:1] op_sel_hi:[1,0]
	s_branch .LBB0_1220

.Lself1_join:
	v_fma_f32 v251, v0, s90, -v236
	ds_read_b128 v[86:89], v81 offset:26688
	ds_read_b128 v[82:85], v81 offset:31296
	v_cmp_ge_f32_e32 vcc, 0x41000000, v251
	s_cmp_eq_u64 vcc, exec
	s_cbranch_scc0 .Llazy1_resc
	v_mov_b32_e32 v235, v236
	v_mov_b32_e32 v0, 1.0

.Lwinf0_join:
	v_fma_f32 v251, v0, s90, -v142
	ds_read_b128 v[84:87], v167 offset:26624
	ds_read_b128 v[80:83], v167 offset:31232
	v_cmp_ge_f32_e32 vcc, 0x41000000, v251
	s_cmp_eq_u64 vcc, exec
	s_cbranch_scc0 .Llazy2_resc
	v_mov_b32_e32 v246, v142
	v_mov_b32_e32 v0, 1.0

.Lwinf1_join:
	v_fma_f32 v251, v14, s90, -v246
	ds_read_b128 v[84:87], v167 offset:26688
	ds_read_b128 v[80:83], v167 offset:31296
	v_cmp_ge_f32_e32 vcc, 0x41000000, v251
	s_cmp_eq_u64 vcc, exec
	s_cbranch_scc0 .Llazy3_resc
	v_mov_b32_e32 v142, v246
	v_mov_b32_e32 v14, 1.0

.Llazy2_resc:
	v_mov_b32_e32 v251, v0
	s_nop 1
	v_permlane32_swap_b32_e32 v0, v251
	v_max_f32_e32 v251, v251, v251
	v_max_f32_e32 v0, v0, v0
	v_max_f32_e32 v0, v0, v251
	v_mul_f32_e32 v0, 0x3e0293ee, v0
	v_max_f32_e32 v251, v142, v142
	v_max_f32_e32 v246, v251, v0
	v_sub_f32_e32 v0, v142, v246
	v_exp_f32_e32 v0, v0
	s_nop 0
	v_pk_mul_f32 v[78:79], v[78:79], v[0:1] op_sel_hi:[1,0]
	v_pk_mul_f32 v[76:77], v[76:77], v[0:1] op_sel_hi:[1,0]
	v_pk_mul_f32 v[74:75], v[74:75], v[0:1] op_sel_hi:[1,0]
	v_pk_mul_f32 v[72:73], v[72:73], v[0:1] op_sel_hi:[1,0]
	v_pk_mul_f32 v[70:71], v[70:71], v[0:1] op_sel_hi:[1,0]
	v_pk_mul_f32 v[68:69], v[68:69], v[0:1] op_sel_hi:[1,0]
	v_pk_mul_f32 v[66:67], v[66:67], v[0:1] op_sel_hi:[1,0]
	v_pk_mul_f32 v[64:65], v[64:65], v[0:1] op_sel_hi:[1,0]
	v_pk_mul_f32 v[62:63], v[62:63], v[0:1] op_sel_hi:[1,0]
	v_pk_mul_f32 v[60:61], v[60:61], v[0:1] op_sel_hi:[1,0]
	v_pk_mul_f32 v[58:59], v[58:59], v[0:1] op_sel_hi:[1,0]
	v_pk_mul_f32 v[56:57], v[56:57], v[0:1] op_sel_hi:[1,0]
	v_pk_mul_f32 v[54:55], v[54:55], v[0:1] op_sel_hi:[1,0]
	v_pk_mul_f32 v[52:53], v[52:53], v[0:1] op_sel_hi:[1,0]
	v_pk_mul_f32 v[50:51], v[50:51], v[0:1] op_sel_hi:[1,0]
	v_pk_mul_f32 v[48:49], v[48:49], v[0:1] op_sel_hi:[1,0]
	v_pk_mul_f32 v[46:47], v[46:47], v[0:1] op_sel_hi:[1,0]
	v_pk_mul_f32 v[44:45], v[44:45], v[0:1] op_sel_hi:[1,0]
	v_pk_mul_f32 v[42:43], v[42:43], v[0:1] op_sel_hi:[1,0]
	v_pk_mul_f32 v[40:41], v[40:41], v[0:1] op_sel_hi:[1,0]
	v_pk_mul_f32 v[38:39], v[38:39], v[0:1] op_sel_hi:[1,0]
	v_pk_mul_f32 v[36:37], v[36:37], v[0:1] op_sel_hi:[1,0]
	v_pk_mul_f32 v[34:35], v[34:35], v[0:1] op_sel_hi:[1,0]
	v_pk_mul_f32 v[32:33], v[32:33], v[0:1] op_sel_hi:[1,0]
	v_pk_mul_f32 v[30:31], v[30:31], v[0:1] op_sel_hi:[1,0]
	v_pk_mul_f32 v[28:29], v[28:29], v[0:1] op_sel_hi:[1,0]
	v_pk_mul_f32 v[26:27], v[26:27], v[0:1] op_sel_hi:[1,0]
	v_pk_mul_f32 v[24:25], v[24:25], v[0:1] op_sel_hi:[1,0]
	v_pk_mul_f32 v[22:23], v[22:23], v[0:1] op_sel_hi:[1,0]
	v_pk_mul_f32 v[20:21], v[20:21], v[0:1] op_sel_hi:[1,0]
	v_pk_mul_f32 v[18:19], v[18:19], v[0:1] op_sel_hi:[1,0]
	v_pk_mul_f32 v[16:17], v[16:17], v[0:1] op_sel_hi:[1,0]
	s_branch .LBB0_1240
.Llazy3_resc:
	v_mov_b32_e32 v251, v14
	s_nop 1
	v_permlane32_swap_b32_e32 v14, v251
	v_max_f32_e32 v251, v251, v251
	v_max_f32_e32 v14, v14, v14
	v_max_f32_e32 v14, v14, v251
	v_mul_f32_e32 v14, 0x3e0293ee, v14
	v_max_f32_e32 v251, v246, v246
	v_max_f32_e32 v142, v251, v14
	v_sub_f32_e32 v14, v246, v142
	v_exp_f32_e32 v14, v14
	s_nop 0
	v_pk_mul_f32 v[78:79], v[78:79], v[14:15] op_sel_hi:[1,0]
	v_pk_mul_f32 v[76:77], v[76:77], v[14:15] op_sel_hi:[1,0]
	v_pk_mul_f32 v[74:75], v[74:75], v[14:15] op_sel_hi:[1,0]
	v_pk_mul_f32 v[72:73], v[72:73], v[14:15] op_sel_hi:[1,0]
	v_pk_mul_f32 v[70:71], v[70:71], v[14:15] op_sel_hi:[1,0]
	v_pk_mul_f32 v[68:69], v[68:69], v[14:15] op_sel_hi:[1,0]
	v_pk_mul_f32 v[66:67], v[66:67], v[14:15] op_sel_hi:[1,0]
	v_pk_mul_f32 v[64:65], v[64:65], v[14:15] op_sel_hi:[1,0]
	v_pk_mul_f32 v[62:63], v[62:63], v[14:15] op_sel_hi:[1,0]
	v_pk_mul_f32 v[60:61], v[60:61], v[14:15] op_sel_hi:[1,0]
	v_pk_mul_f32 v[58:59], v[58:59], v[14:15] op_sel_hi:[1,0]
	v_pk_mul_f32 v[56:57], v[56:57], v[14:15] op_sel_hi:[1,0]
	v_pk_mul_f32 v[54:55], v[54:55], v[14:15] op_sel_hi:[1,0]
	v_pk_mul_f32 v[52:53], v[52:53], v[14:15] op_sel_hi:[1,0]
	v_pk_mul_f32 v[50:51], v[50:51], v[14:15] op_sel_hi:[1,0]
	v_pk_mul_f32 v[48:49], v[48:49], v[14:15] op_sel_hi:[1,0]
	v_pk_mul_f32 v[46:47], v[46:47], v[14:15] op_sel_hi:[1,0]
	v_pk_mul_f32 v[44:45], v[44:45], v[14:15] op_sel_hi:[1,0]
	v_pk_mul_f32 v[42:43], v[42:43], v[14:15] op_sel_hi:[1,0]
	v_pk_mul_f32 v[40:41], v[40:41], v[14:15] op_sel_hi:[1,0]
	v_pk_mul_f32 v[38:39], v[38:39], v[14:15] op_sel_hi:[1,0]
	v_pk_mul_f32 v[36:37], v[36:37], v[14:15] op_sel_hi:[1,0]
	v_pk_mul_f32 v[34:35], v[34:35], v[14:15] op_sel_hi:[1,0]
	v_pk_mul_f32 v[32:33], v[32:33], v[14:15] op_sel_hi:[1,0]
	v_pk_mul_f32 v[30:31], v[30:31], v[14:15] op_sel_hi:[1,0]
	v_pk_mul_f32 v[28:29], v[28:29], v[14:15] op_sel_hi:[1,0]
	v_pk_mul_f32 v[26:27], v[26:27], v[14:15] op_sel_hi:[1,0]
	v_pk_mul_f32 v[24:25], v[24:25], v[14:15] op_sel_hi:[1,0]
	v_pk_mul_f32 v[22:23], v[22:23], v[14:15] op_sel_hi:[1,0]
	v_pk_mul_f32 v[20:21], v[20:21], v[14:15] op_sel_hi:[1,0]
	v_pk_mul_f32 v[18:19], v[18:19], v[14:15] op_sel_hi:[1,0]
	v_pk_mul_f32 v[16:17], v[16:17], v[14:15] op_sel_hi:[1,0]
	s_branch .LBB0_1244
